# grid barrier poll interval s_sleep 32 -> 2
# speedup vs baseline: 1.0049x; 1.0049x over previous
.LBB0_103:
	global_load_dword v3, v2, s[78:79] offset:256 sc1
	s_mov_b64 s[6:7], -1
	s_waitcnt vmcnt(0)
	v_cmp_ne_u32_e32 vcc, v3, v1
	s_cbranch_vccnz .LBB0_102
	s_sleep 2
	global_load_dword v3, v2, s[78:79] offset:256 sc1
	s_waitcnt vmcnt(0)
	v_cmp_eq_u32_e32 vcc, v3, v1
	s_cbranch_vccz .LBB0_102
	s_sleep 2
	global_load_dword v3, v2, s[78:79] offset:256 sc1
	s_waitcnt vmcnt(0)
	v_cmp_eq_u32_e32 vcc, v3, v1
	s_cbranch_vccz .LBB0_102
	s_sleep 2
	global_load_dword v3, v2, s[78:79] offset:256 sc1
	s_waitcnt vmcnt(0)
	v_cmp_eq_u32_e32 vcc, v3, v1
	s_cbranch_vccz .LBB0_102
	s_sleep 2
	global_load_dword v3, v2, s[78:79] offset:256 sc1
	s_waitcnt vmcnt(0)
	v_cmp_eq_u32_e32 vcc, v3, v1
	s_cbranch_vccz .LBB0_102
	s_add_i32 s8, s8, -5
	s_cmp_eq_u32 s8, 0
	s_cselect_b64 s[6:7], -1, 0
	s_sleep 2
	s_branch .LBB0_102
